# weight conversion: LDS tile double-buffered, one workgroup barrier per tile instead of two
# baseline (speedup 1.0000x reference)
.LBB0_32:
	s_or_b64 exec, exec, s[4:5]
	s_cmpk_gt_i32 s2, 0xc8f
	s_cselect_b64 s[4:5], -1, 0
	v_writelane_b32 v249, s4, 1
	s_and_b64 vcc, exec, s[4:5]
	s_nop 0
	v_writelane_b32 v249, s5, 2
	s_cbranch_vccnz .LBB0_57
	s_load_dwordx4 s[4:7], s[46:47], 0x88
	s_load_dwordx4 s[8:11], s[46:47], 0xc0
	s_load_dwordx2 s[16:17], s[46:47], 0x78
	s_load_dwordx4 s[12:15], s[46:47], 0x30
	v_mov_b64_e32 v[0:1], s[0:1]
	s_mov_b64 s[18:19], 0x1900000
	s_mov_b32 s21, 0
	s_mov_b64 s[22:23], 0x18e0000
	s_mov_b64 s[24:25], 0x18c0000
	s_mov_b64 s[26:27], 0x10c0000
	s_mov_b64 s[28:29], 0x8c0000
	s_mov_b64 s[30:31], 0x6c0000
	v_mov_b32_e32 v3, 0
	s_movk_i32 s33, 0x104
	s_mov_b32 s40, s2
	s_mov_b32 s100, 0
	s_branch .LBB0_36

.LBB0_35:
	s_lshr_b32 s38, s20, 6
	v_cvt_f32_u32_e32 v2, s38
	s_sub_i32 s43, 0, s38
	s_abs_i32 s42, s41
	s_ashr_i32 s39, s41, 31
	v_rcp_iflag_f32_e32 v2, v2
	v_mov_b32_e32 v16, v154
	v_mul_f32_e32 v2, 0x4f7ffffe, v2
	v_cvt_u32_f32_e32 v2, v2
	v_ashrrev_i32_e32 v17, 4, v16
	v_readfirstlane_b32 s44, v2
	s_mul_i32 s43, s43, s44
	s_mul_hi_u32 s43, s44, s43
	s_add_i32 s44, s44, s43
	s_mul_hi_u32 s43, s42, s44
	s_mul_i32 s44, s43, s38
	s_sub_i32 s42, s42, s44
	s_add_i32 s45, s43, 1
	s_sub_i32 s44, s42, s38
	s_cmp_ge_u32 s42, s38
	s_cselect_b32 s43, s45, s43
	s_cselect_b32 s42, s44, s42
	s_add_i32 s44, s43, 1
	s_cmp_ge_u32 s42, s38
	s_cselect_b32 s42, s44, s43
	s_xor_b32 s42, s42, s39
	s_sub_i32 s39, s42, s39
	s_mul_i32 s42, s39, s38
	s_lshl_b32 s38, s39, 6
	s_sub_i32 s39, s41, s42
	s_lshl_b32 s42, s39, 6
	s_ashr_i32 s43, s42, 31
	s_lshl_b64 s[44:45], s[42:43], 2
	s_add_u32 s36, s36, s44
	v_lshlrev_b32_e32 v2, 4, v16
	s_addc_u32 s37, s37, s45
	v_and_b32_e32 v2, 0xf0, v2
	v_add_u32_e32 v12, s38, v17
	v_lshl_add_u64 v[10:11], s[36:37], 0, v[2:3]
	v_mad_u64_u32 v[6:7], s[36:37], v12, s20, 0
	v_ashrrev_i32_e32 v9, 31, v12
	v_mov_b32_e32 v8, v7
	v_add_u32_e32 v12, 32, v12
	v_mad_u64_u32 v[8:9], s[36:37], v9, s20, v[8:9]
	v_ashrrev_i32_e32 v15, 31, v12
	v_mad_u64_u32 v[12:13], s[36:37], v12, s20, 0
	v_mov_b32_e32 v7, v8
	v_mov_b32_e32 v14, v13
	v_lshl_add_u64 v[6:7], v[6:7], 2, v[10:11]
	v_mad_u64_u32 v[14:15], s[36:37], v15, s20, v[14:15]
	global_load_dwordx4 v[6:9], v[6:7], off
	v_mov_b32_e32 v13, v14
	v_lshl_add_u64 v[10:11], v[12:13], 2, v[10:11]
	global_load_dwordx4 v[10:13], v[10:11], off
	v_lshlrev_b32_e32 v15, 3, v16
	v_ashrrev_i32_e32 v14, 3, v16
	v_mul_lo_u32 v16, v17, s33
	v_and_b32_e32 v17, 56, v15
	v_lshlrev_b32_e32 v15, 2, v14
	v_add3_u32 v16, s100, v2, v16
	v_mul_u32_u24_e32 v2, 0x104, v17
	v_add3_u32 v20, s100, v15, v2
	s_xor_b32 s100, s100, 0x8000
	v_add_u32_e32 v2, s42, v14
	v_ashrrev_i32_e32 v22, 31, v2
	v_add_u32_e32 v18, 0x2080, v16
	v_add_u32_e32 v19, 0x2088, v16
	v_add_u32_e32 v21, 0x400, v20
	v_mul_lo_u32 v23, s35, v2
	v_mad_u64_u32 v[14:15], s[36:37], s34, v2, 0
	v_mul_lo_u32 v2, s34, v22
	v_add3_u32 v15, v15, v2, v23
	s_ashr_i32 s39, s38, 31
	v_lshl_add_u64 v[4:5], v[14:15], 1, v[4:5]
	s_add_i32 s40, s40, s66
	v_lshlrev_b32_e32 v2, 1, v17
	v_lshl_add_u64 v[4:5], s[38:39], 1, v[4:5]
	s_cmpk_lt_i32 s40, 0xc90
	v_lshl_add_u64 v[14:15], v[4:5], 0, v[2:3]
	s_waitcnt vmcnt(1)
	ds_write2_b32 v16, v6, v7 offset1:1
	ds_write2_b32 v16, v8, v9 offset0:2 offset1:3
	s_waitcnt vmcnt(0)
	ds_write2_b32 v18, v10, v11 offset1:1
	ds_write2_b32 v19, v12, v13 offset1:1
	s_waitcnt lgkmcnt(0)
	s_barrier
	ds_read2_b32 v[6:7], v20 offset1:65
	ds_read2_b32 v[8:9], v20 offset0:130 offset1:195
	ds_read2_b32 v[10:11], v21 offset0:4 offset1:69
	ds_read2_b32 v[12:13], v21 offset0:134 offset1:199
	s_waitcnt lgkmcnt(3)
	v_cvt_pk_bf16_f32 v4, v6, v7
	s_waitcnt lgkmcnt(2)
	v_cvt_pk_bf16_f32 v5, v8, v9
	s_waitcnt lgkmcnt(1)
	v_cvt_pk_bf16_f32 v6, v10, v11
	s_waitcnt lgkmcnt(0)
	v_cvt_pk_bf16_f32 v7, v12, v13
	global_store_dwordx4 v[14:15], v[4:7], off
	s_cbranch_scc0 .LBB0_57

.LBB0_66:
	v_mov_b64_e32 v[0:1], v[132:133]
	s_mul_i32 s52, s20, 0x6000
	v_lshl_add_u64 v[0:1], s[52:53], 2, v[0:1]
	s_mov_b64 s[6:7], 0x1fa00000
	v_lshl_add_u64 v[136:137], v[0:1], 0, s[6:7]
	v_readlane_b32 s6, v249, 1
	v_readlane_b32 s7, v249, 2
	s_or_b64 s[6:7], s[6:7], s[4:5]
	s_mov_b32 s64, s20
	s_and_b64 vcc, exec, s[6:7]
	s_mov_b32 s15, s2
	s_mov_b32 s100, 0
	s_cbranch_vccz .LBB0_79

.LBB0_78:
	s_lshr_b32 s46, s52, 6
	v_cvt_f32_u32_e32 v2, s46
	s_sub_i32 s56, 0, s46
	s_abs_i32 s55, s54
	s_ashr_i32 s47, s54, 31
	v_rcp_iflag_f32_e32 v2, v2
	v_mov_b32_e32 v12, v154
	v_mul_f32_e32 v2, 0x4f7ffffe, v2
	v_cvt_u32_f32_e32 v2, v2
	v_ashrrev_i32_e32 v13, 4, v12
	v_readfirstlane_b32 s57, v2
	s_mul_i32 s56, s56, s57
	s_mul_hi_u32 s56, s57, s56
	s_add_i32 s57, s57, s56
	s_mul_hi_u32 s56, s55, s57
	s_mul_i32 s57, s56, s46
	s_sub_i32 s55, s55, s57
	s_add_i32 s58, s56, 1
	s_sub_i32 s57, s55, s46
	s_cmp_ge_u32 s55, s46
	s_cselect_b32 s56, s58, s56
	s_cselect_b32 s55, s57, s55
	s_add_i32 s57, s56, 1
	s_cmp_ge_u32 s55, s46
	s_cselect_b32 s55, s57, s56
	s_xor_b32 s55, s55, s47
	s_sub_i32 s47, s55, s47
	s_mul_i32 s55, s47, s46
	s_lshl_b32 s46, s47, 6
	s_sub_i32 s47, s54, s55
	s_lshl_b32 s54, s47, 6
	s_ashr_i32 s55, s54, 31
	s_lshl_b64 s[56:57], s[54:55], 2
	s_add_u32 s44, s44, s56
	v_lshlrev_b32_e32 v2, 4, v12
	s_addc_u32 s45, s45, s57
	v_and_b32_e32 v134, 0xf0, v2
	v_add_u32_e32 v8, s46, v13
	v_lshl_add_u64 v[6:7], s[44:45], 0, v[134:135]
	v_mad_u64_u32 v[2:3], s[44:45], v8, s52, 0
	v_ashrrev_i32_e32 v5, 31, v8
	v_mov_b32_e32 v4, v3
	v_add_u32_e32 v8, 32, v8
	v_mad_u64_u32 v[4:5], s[44:45], v5, s52, v[4:5]
	v_ashrrev_i32_e32 v11, 31, v8
	v_mad_u64_u32 v[8:9], s[44:45], v8, s52, 0
	v_mov_b32_e32 v3, v4
	v_mov_b32_e32 v10, v9
	v_lshl_add_u64 v[2:3], v[2:3], 2, v[6:7]
	v_mad_u64_u32 v[10:11], s[44:45], v11, s52, v[10:11]
	global_load_dwordx4 v[2:5], v[2:3], off
	v_mov_b32_e32 v9, v10
	v_lshl_add_u64 v[6:7], v[8:9], 2, v[6:7]
	global_load_dwordx4 v[6:9], v[6:7], off
	v_lshlrev_b32_e32 v11, 3, v12
	s_movk_i32 s44, 0x104
	v_ashrrev_i32_e32 v10, 3, v12
	v_mul_lo_u32 v12, v13, s44
	v_and_b32_e32 v13, 56, v11
	v_lshlrev_b32_e32 v11, 2, v10
	v_mul_u32_u24_e32 v14, 0x104, v13
	v_add_u32_e32 v10, s54, v10
	v_add3_u32 v12, s100, v134, v12
	v_add3_u32 v14, s100, v11, v14
	s_xor_b32 s100, s100, 0x8000
	v_ashrrev_i32_e32 v18, 31, v10
	v_add_u32_e32 v15, 0x2080, v12
	v_add_u32_e32 v16, 0x2088, v12
	v_add_u32_e32 v17, 0x400, v14
	v_mul_lo_u32 v19, s7, v10
	v_mad_u64_u32 v[10:11], s[44:45], s6, v10, 0
	v_mul_lo_u32 v18, s6, v18
	v_add3_u32 v11, v11, v18, v19
	s_ashr_i32 s47, s46, 31
	v_lshl_add_u64 v[0:1], v[10:11], 1, v[0:1]
	s_add_i32 s15, s15, s66
	v_lshlrev_b32_e32 v134, 1, v13
	v_lshl_add_u64 v[0:1], s[46:47], 1, v[0:1]
	v_readlane_b32 s56, v248, 20
	s_cmpk_lt_i32 s15, 0xc90
	v_lshl_add_u64 v[10:11], v[0:1], 0, v[134:135]
	v_readlane_b32 s57, v248, 21
	s_waitcnt vmcnt(1)
	ds_write2_b32 v12, v2, v3 offset1:1
	ds_write2_b32 v12, v4, v5 offset0:2 offset1:3
	s_waitcnt vmcnt(0)
	ds_write2_b32 v15, v6, v7 offset1:1
	ds_write2_b32 v16, v8, v9 offset1:1
	s_waitcnt lgkmcnt(0)
	s_barrier
	ds_read2_b32 v[2:3], v14 offset1:65
	ds_read2_b32 v[4:5], v14 offset0:130 offset1:195
	ds_read2_b32 v[6:7], v17 offset0:4 offset1:69
	ds_read2_b32 v[8:9], v17 offset0:134 offset1:199
	s_waitcnt lgkmcnt(3)
	v_cvt_pk_bf16_f32 v0, v2, v3
	s_waitcnt lgkmcnt(2)
	v_cvt_pk_bf16_f32 v1, v4, v5
	s_waitcnt lgkmcnt(1)
	v_cvt_pk_bf16_f32 v2, v6, v7
	s_waitcnt lgkmcnt(0)
	v_cvt_pk_bf16_f32 v3, v8, v9
	global_store_dwordx4 v[10:11], v[0:3], off
	s_cbranch_scc0 .LBB0_67
